# scan chunk prefetch addressing hoisted out of the step loop (32-bit per-thread offsets + scalar chunk term), on top of park packing and attention prio
# speedup vs baseline: 1.0048x; 1.0048x over previous
; __device__ __forceinline__ void scan_unit(const int unit, const Args& a, unsigned char* lds, const int mk_wid) {
;     ...
;     u16* qe = (u16*)(lds + L_QE); u16* ke = (u16*)(lds + L_KE); u16* am = (u16*)(lds + L_AM);
;     float* las = (float*)(lds + L_LAS); float* gs = (float*)(lds + L_GS); float* dl = (float*)(lds + L_DL);
;     const int ldsb = (int)(uintptr_t)lds;
;     u16* ot = (u16*)(lds + L_LAS);
;     int pend_cc = -1;
;     ...
;     f32x16 S[4]; S[0] = f32x16{}; S[1] = f32x16{}; S[2] = f32x16{}; S[3] = f32x16{};
;     bf16x8 qraw[2], kraw[2], vraw[4]; bf16x8 lraw = bf16x8{};
;     ...
;     GLA_LOAD(0);
.LBB0_416:
	s_or_b64 exec, exec, s[22:23]
	s_mov_b32 s4, 0x2a00000
	s_and_b64 s[20:21], s[2:3], exec
	s_cselect_b32 s4, s4, 0x1aa00000
	s_add_u32 s4, s38, s4
	s_addc_u32 s9, s39, 0
	s_lshl_b64 s[20:21], s[18:19], 11
	s_lshl_b32 s18, s35, 1
	s_add_u32 s18, s4, s18
	s_addc_u32 s19, s9, 0
	s_lshr_b32 s4, s33, 8
	s_lshl_b32 s9, s4, 10
	s_add_i32 s44, s9, 0
	s_lshl_b32 s4, s4, 14
	s_add_i32 s9, 0, 0x16c00
	s_add_i32 s45, s9, s4
	s_lshl_b32 s22, s34, 2
	s_add_i32 s44, s44, 0x1ec00
	s_add_i32 s45, s45, s22
	s_lshl_b32 s22, s27, 1
	s_add_u32 s22, s38, s22
	s_addc_u32 s23, s39, 0
	s_add_u32 s22, s22, 0xd600000
	s_addc_u32 s23, s23, 0
	s_cmpk_lt_u32 s33, 0x100
	v_lshl_add_u64 v[152:153], v[0:1], 1, s[24:25]
	s_cselect_b64 s[24:25], -1, 0
	s_lshl_b32 s27, s70, 4
	s_and_b32 s46, s27, 0x3fffffe0
	s_lshl_b32 s27, s70, 5
	s_and_b32 s47, s27, 32
	s_cmp_lg_u32 0, -1
	s_cselect_b32 s27, 0, 0
	s_add_i32 s4, s27, s4
	s_lshl_b32 s26, s26, 9
	s_add_i32 s48, s4, s26
	v_mov_b32_e32 v155, 0
	s_waitcnt vmcnt(0)
	v_mov_b32_e32 v128, 0
	v_cvt_pk_bf16_f32 v108, v5, v7
	v_cvt_pk_bf16_f32 v109, v2, v8
	v_cvt_pk_bf16_f32 v110, v3, v4
	v_cvt_pk_bf16_f32 v111, v6, v9
	s_mov_b32 s34, -1
	s_add_i32 s48, s48, 0xc800
	s_add_i32 s49, s9, s72
	s_mov_b32 s50, 38
	s_movk_i32 s51, 0x110
	s_movk_i32 s52, 0x80
	s_add_i32 s53, 0, 0x1ec00
	s_mov_b32 s54, 0xbfb8aa3b
	s_add_i32 s55, 0, 0x1f400
	s_movk_i32 s56, 0x1100
	s_add_i32 s57, 0, 0x14800
	v_mov_b32_e32 v129, v128
	v_mov_b32_e32 v130, v128
	v_mov_b32_e32 v131, v128
	v_mov_b32_e32 v132, v128
	v_mov_b32_e32 v133, v128
	v_mov_b32_e32 v134, v128
	v_mov_b32_e32 v135, v128
	v_mov_b32_e32 v0, v155
	v_mov_b32_e32 v1, v155
	v_mov_b32_e32 v2, v155
	v_mov_b32_e32 v3, v155
	v_mov_b32_e32 v4, v155
	v_mov_b32_e32 v5, v155
	v_mov_b32_e32 v6, v155
	v_mov_b32_e32 v7, v155
	v_mov_b32_e32 v8, v155
	v_mov_b32_e32 v9, v155
	v_mov_b32_e32 v10, v155
	v_mov_b32_e32 v11, v155
	v_mov_b32_e32 v12, v155
	v_mov_b32_e32 v13, v155
	v_mov_b32_e32 v14, v155
	v_mov_b32_e32 v15, v155
	v_mov_b32_e32 v16, v155
	v_mov_b32_e32 v17, v155
	v_mov_b32_e32 v18, v155
	v_mov_b32_e32 v19, v155
	v_mov_b32_e32 v20, v155
	v_mov_b32_e32 v21, v155
	v_mov_b32_e32 v22, v155
	v_mov_b32_e32 v23, v155
	v_mov_b32_e32 v24, v155
	v_mov_b32_e32 v25, v155
	v_mov_b32_e32 v26, v155
	v_mov_b32_e32 v27, v155
	v_mov_b32_e32 v28, v155
	v_mov_b32_e32 v29, v155
	v_mov_b32_e32 v30, v155
	v_mov_b32_e32 v31, v155
	v_mov_b32_e32 v32, v155
	v_mov_b32_e32 v33, v155
	v_mov_b32_e32 v34, v155
	v_mov_b32_e32 v35, v155
	v_mov_b32_e32 v36, v155
	v_mov_b32_e32 v37, v155
	v_mov_b32_e32 v38, v155
	v_mov_b32_e32 v39, v155
	v_mov_b32_e32 v40, v155
	v_mov_b32_e32 v41, v155
	v_mov_b32_e32 v42, v155
	v_mov_b32_e32 v43, v155
	v_mov_b32_e32 v44, v155
	v_mov_b32_e32 v45, v155
	v_mov_b32_e32 v46, v155
	v_mov_b32_e32 v47, v155
	v_mov_b32_e32 v48, v155
	v_mov_b32_e32 v49, v155
	v_mov_b32_e32 v50, v155
	v_mov_b32_e32 v51, v155
	v_mov_b32_e32 v52, v155
	v_mov_b32_e32 v53, v155
	v_mov_b32_e32 v54, v155
	v_mov_b32_e32 v55, v155
	v_mov_b32_e32 v56, v155
	v_mov_b32_e32 v57, v155
	v_mov_b32_e32 v58, v155
	v_mov_b32_e32 v59, v155
	v_mov_b32_e32 v60, v155
	v_mov_b32_e32 v61, v155
	v_mov_b32_e32 v62, v155
	v_mov_b32_e32 v63, v155
	v_mbcnt_lo_u32_b32 v64, -1, 0
	v_mbcnt_hi_u32_b32 v64, -1, v64
	v_add_u32_e32 v64, s72, v64
	v_lshrrev_b32_e32 v65, 4, v64
	v_and_b32_e32 v67, 15, v64
	v_lshlrev_b32_e32 v67, 4, v67
	v_sub_u32_e32 v66, 63, v65
	v_cndmask_b32_e64 v66, v66, v65, s[2:3]
	v_add_u32_e32 v66, s12, v66
	v_lshl_add_u32 v245, v66, 10, v67
	v_add_u32_e32 v68, 32, v65
	v_sub_u32_e32 v69, 31, v65
	v_cndmask_b32_e64 v68, v69, v68, s[2:3]
	v_add_u32_e32 v68, s12, v68
	v_lshl_add_u32 v246, v68, 10, v67
	v_lshrrev_b32_e32 v65, 5, v64
	v_and_b32_e32 v67, 31, v64
	v_lshlrev_b32_e32 v67, 4, v67
	v_add_u32_e32 v68, 0, v65
	v_sub_u32_e32 v69, 63, v65
	v_cndmask_b32_e64 v68, v69, v68, s[2:3]
	v_add_u32_e32 v68, s12, v68
	v_lshl_add_u32 v247, v68, 11, v67
	v_add_u32_e32 v68, 16, v65
	v_sub_u32_e32 v69, 47, v65
	v_cndmask_b32_e64 v68, v69, v68, s[2:3]
	v_add_u32_e32 v68, s12, v68
	v_lshl_add_u32 v248, v68, 11, v67
	v_add_u32_e32 v68, 32, v65
	v_sub_u32_e32 v69, 31, v65
	v_cndmask_b32_e64 v68, v69, v68, s[2:3]
	v_add_u32_e32 v68, s12, v68
	v_lshl_add_u32 v249, v68, 11, v67
	v_add_u32_e32 v68, 48, v65
	v_sub_u32_e32 v69, 15, v65
	v_cndmask_b32_e64 v68, v69, v68, s[2:3]
	v_add_u32_e32 v68, s12, v68
	v_lshl_add_u32 v250, v68, 11, v67
	v_lshrrev_b32_e32 v65, 1, v64
	v_sub_u32_e32 v69, 63, v65
	v_cndmask_b32_e64 v68, v69, v65, s[2:3]
	v_add_u32_e32 v68, s12, v68
	v_and_b32_e32 v67, 1, v64
	v_lshlrev_b32_e32 v67, 4, v67
	v_lshl_add_u32 v251, v68, 6, v67

; __device__ __forceinline__ unsigned pk2(float lo, float hi) { f32x2_t v = {lo, hi}; bf16x2_t b = __builtin_convertvector(v, bf16x2_t); return __builtin_bit_cast(unsigned, b); }
; #define OPAQUE_TID(name) int name = MK_TID; asm volatile("" : "+v"(name))
; __device__ __forceinline__ void scan_unit(const int unit, const Args& a, unsigned char* lds, const int mk_wid) {
;     ...
;         if (lat) {
;             if (wid < 4) { OPAQUE_TID(t_); const int r32 = t_ & 31, hi = (t_ >> 5) & 1;
;                 const int jt = wid >> 1, it = wid & 1; f32x16 ct = f32x16{};
;                 const u16* kp = ke + (jt * 32 + r32) * QP + hi * 8; const u16* qp = qe + (it * 32 + r32) * QP + hi * 8;
; #pragma unroll
;                 for (int kb = 0; kb < 8; ++kb) ct = __builtin_amdgcn_mfma_f32_32x32x16_bf16(*(const bf16x8*)(kp + kb * 16), *(const bf16x8*)(qp + kb * 16), ct, 0, 0, 0);
;                 const int i = it * 32 + r32;
; #pragma unroll
;                 for (int rg = 0; rg < 4; ++rg) { const int j0 = jt * 32 + 8 * rg + 4 * hi;
;                     const float x0 = (j0 + 0 <= i) ? ct[4 * rg + 0] : 0.f, x1 = (j0 + 1 <= i) ? ct[4 * rg + 1] : 0.f, x2 = (j0 + 2 <= i) ? ct[4 * rg + 2] : 0.f, x3 = (j0 + 3 <= i) ? ct[4 * rg + 3] : 0.f;
;                     v2u w; w.x = pk2(x0, x1); w.y = pk2(x2, x3); *(v2u*)(am + i * AP + j0) = w; } }
.LBB0_426:
	s_lshl_b32 s26, s34, 16
	s_lshl_b32 s27, s34, 17
	s_lshl_b32 s35, s34, 12
	v_add_u32_e32 v64, s26, v245
	v_add_u32_e32 v65, s26, v246
	global_load_dwordx4 v[100:103], v64, s[14:15]
	s_cmp_lt_i32 s34, 4
	s_cbranch_scc1 .Lscan_pf_noq
	global_load_dwordx4 v[128:131], v64, s[22:23]
	global_load_dwordx4 v[104:107], v65, s[14:15]
	global_load_dwordx4 v[132:135], v65, s[22:23]
	s_branch .Lscan_pf_v
.Lscan_pf_noq:
	global_load_dwordx4 v[104:107], v65, s[14:15]
	v_mov_b32_e32 v128, 0
	v_mov_b32_e32 v129, 0
	v_mov_b32_e32 v130, 0
	v_mov_b32_e32 v131, 0
	v_mov_b32_e32 v132, 0
	v_mov_b32_e32 v133, 0
	v_mov_b32_e32 v134, 0
	v_mov_b32_e32 v135, 0
.Lscan_pf_v:
	v_add_u32_e32 v66, s27, v247
	v_add_u32_e32 v67, s27, v248
	v_add_u32_e32 v68, s27, v249
	v_add_u32_e32 v69, s27, v250
	global_load_dwordx4 v[112:115], v66, s[16:17]
	global_load_dwordx4 v[116:119], v67, s[16:17]
	global_load_dwordx4 v[120:123], v68, s[16:17]
	global_load_dwordx4 v[124:127], v69, s[16:17]
	s_cmp_lt_u32 s70, 2
	s_cbranch_scc0 .Lscan_pf_nolr
	v_add_u32_e32 v70, s35, v251
	v_mov_b32_e32 v71, 0
	v_lshl_add_u64 v[70:71], v[152:153], 0, v[70:71]
	global_load_dwordx4 v[96:99], v[70:71], off
.Lscan_pf_nolr:
.LBB0_435:
	s_cmp_gt_u32 s5, 3
	s_cselect_b32 s4, 39, 3
	s_add_i32 s4, s4, s50
	s_sub_i32 s4, s4, 38
	s_and_b64 s[26:27], s[2:3], exec
	s_cselect_b32 s42, s5, s4
	s_cmp_gt_i32 s42, 3
	s_cselect_b64 s[26:27], -1, 0
	s_cmp_lt_i32 s42, 4
	s_cselect_b64 s[34:35], -1, 0
	s_and_b64 vcc, exec, s[34:35]
	s_waitcnt lgkmcnt(0)
	s_barrier
	s_cbranch_vccnz .LBB0_439
	s_andn2_b64 vcc, exec, s[24:25]
	s_cbranch_vccnz .LBB0_438
	v_mbcnt_lo_u32_b32 v64, -1, 0
	v_mbcnt_hi_u32_b32 v64, -1, v64
	s_nop 0
	v_add_u32_e32 v64, s72, v64
	s_nop 0
	v_and_b32_e32 v68, 31, v64
	v_bfe_u32 v154, v64, 5, 1
	v_or_b32_e32 v64, s46, v68
	v_mul_lo_u32 v64, v64, s51
	v_lshlrev_b32_e32 v69, 4, v154
	v_add3_u32 v157, 0, v64, v69
	ds_read_b128 v[64:67], v157 offset:17408
	v_or_b32_e32 v158, s47, v68
	v_mul_u32_u24_e32 v68, 0x110, v158
	v_add3_u32 v159, 0, v68, v69
	ds_read_b128 v[68:71], v159
	ds_read_b128 v[80:83], v157 offset:17440
	ds_read_b128 v[84:87], v159 offset:32
	s_waitcnt lgkmcnt(2)
	v_mfma_f32_32x32x16_bf16 v[64:79], v[64:67], v[68:71], 0
	v_lshl_or_b32 v154, v154, 2, s46
	v_cmp_le_u32_e32 vcc, v154, v158
	v_or_b32_e32 v161, 2, v154
	v_or_b32_e32 v162, 3, v154
	v_or_b32_e32 v164, 8, v154
	v_mul_u32_u24_e32 v160, 0x90, v158
	v_lshlrev_b32_e32 v163, 1, v154
	s_waitcnt lgkmcnt(0)
	v_mfma_f32_32x32x16_bf16 v[64:79], v[80:83], v[84:87], v[64:79]
	ds_read_b128 v[80:83], v157 offset:17472
	ds_read_b128 v[84:87], v159 offset:64
	ds_read_b128 v[88:91], v157 offset:17504
	ds_read_b128 v[92:95], v159 offset:96
	s_waitcnt lgkmcnt(2)
	v_mfma_f32_32x32x16_bf16 v[64:79], v[80:83], v[84:87], v[64:79]
	s_waitcnt lgkmcnt(0)
	v_mfma_f32_32x32x16_bf16 v[64:79], v[88:91], v[92:95], v[64:79]
	ds_read_b128 v[80:83], v157 offset:17536
	ds_read_b128 v[84:87], v159 offset:128
	ds_read_b128 v[88:91], v157 offset:17568
	ds_read_b128 v[92:95], v159 offset:160
	s_waitcnt lgkmcnt(2)
	v_mfma_f32_32x32x16_bf16 v[64:79], v[80:83], v[84:87], v[64:79]
	ds_read_b128 v[80:83], v157 offset:17600
	ds_read_b128 v[84:87], v159 offset:192
	s_waitcnt lgkmcnt(2)
	v_mfma_f32_32x32x16_bf16 v[64:79], v[88:91], v[92:95], v[64:79]
	ds_read_b128 v[88:91], v157 offset:17632
	ds_read_b128 v[92:95], v159 offset:224
	s_waitcnt lgkmcnt(2)
	v_mfma_f32_32x32x16_bf16 v[64:79], v[80:83], v[84:87], v[64:79]
	v_or_b32_e32 v80, 10, v154
	v_or_b32_e32 v81, 11, v154
	v_or_b32_e32 v82, 16, v154
	v_or_b32_e32 v83, 18, v154
	v_or_b32_e32 v84, 19, v154
	v_or_b32_e32 v85, 24, v154
	v_add3_u32 v86, s57, v160, v163
	s_waitcnt lgkmcnt(0)
	v_mfma_f32_32x32x16_bf16 v[64:79], v[88:91], v[92:95], v[64:79]
	s_nop 11
	v_cndmask_b32_e32 v64, 0, v64, vcc
	v_cmp_lt_u32_e32 vcc, v154, v158
	s_nop 1
	v_cndmask_b32_e32 v65, 0, v65, vcc
	v_cmp_le_u32_e32 vcc, v161, v158
	v_cvt_pk_bf16_f32 v64, v64, v65
	s_nop 0
	v_cndmask_b32_e32 v66, 0, v66, vcc
	v_cmp_le_u32_e32 vcc, v162, v158
	s_nop 1
	v_cndmask_b32_e32 v67, 0, v67, vcc
	v_cmp_le_u32_e32 vcc, v164, v158
	v_cvt_pk_bf16_f32 v65, v66, v67
	s_nop 0
	v_cndmask_b32_e32 v68, 0, v68, vcc
	v_cmp_lt_u32_e32 vcc, v164, v158
	s_nop 1
	v_cndmask_b32_e32 v69, 0, v69, vcc
	v_cmp_le_u32_e32 vcc, v80, v158
	v_cvt_pk_bf16_f32 v66, v68, v69
	s_nop 0
	v_cndmask_b32_e32 v70, 0, v70, vcc
	v_cmp_le_u32_e32 vcc, v81, v158
	s_nop 1
	v_cndmask_b32_e32 v71, 0, v71, vcc
	v_cmp_le_u32_e32 vcc, v82, v158
	v_cvt_pk_bf16_f32 v67, v70, v71
	ds_write2_b64 v86, v[64:65], v[66:67] offset1:2
	v_cndmask_b32_e32 v72, 0, v72, vcc
	v_cmp_lt_u32_e32 vcc, v82, v158
	v_or_b32_e32 v65, 26, v154
	v_or_b32_e32 v66, 27, v154
	v_cndmask_b32_e32 v73, 0, v73, vcc
	v_cmp_le_u32_e32 vcc, v83, v158
	v_cvt_pk_bf16_f32 v68, v72, v73
	s_nop 0
	v_cndmask_b32_e32 v74, 0, v74, vcc
	v_cmp_le_u32_e32 vcc, v84, v158
	s_nop 1
	v_cndmask_b32_e32 v75, 0, v75, vcc
	v_cmp_le_u32_e32 vcc, v85, v158
	v_cvt_pk_bf16_f32 v69, v74, v75
	s_nop 0
	v_cndmask_b32_e32 v76, 0, v76, vcc
	v_cmp_lt_u32_e32 vcc, v85, v158
	s_nop 1
	v_cndmask_b32_e32 v64, 0, v77, vcc
	v_cmp_le_u32_e32 vcc, v65, v158
	v_cvt_pk_bf16_f32 v64, v76, v64
	s_nop 0
	v_cndmask_b32_e32 v65, 0, v78, vcc
	v_cmp_le_u32_e32 vcc, v66, v158
	s_nop 1
	v_cndmask_b32_e32 v66, 0, v79, vcc
	v_cvt_pk_bf16_f32 v65, v65, v66
	ds_write2_b64 v86, v[68:69], v[64:65] offset0:4 offset1:6
